# v86 + HGRN2: V^T LDS writes moved to the start of step 2 and the next chunk's two v loads issued there; no load burst left at the end of step 2
# baseline (speedup 1.0000x reference)
.LBB0_1169:
	s_waitcnt vmcnt(5)
	v_pk_add_f32 v[118:119], v[92:93], 0 op_sel_hi:[1,0]
	v_add_u32_e32 v58, s18, v132
	v_pk_add_f32 v[116:117], v[118:119], v[80:81]
	v_add_u32_e32 v160, 0, v132
	v_pk_add_f32 v[114:115], v[116:117], v[82:83]
	v_readlane_b32 s6, v254, 20
	v_pk_add_f32 v[112:113], v[114:115], v[86:87]
	v_readlane_b32 s7, v254, 21
	v_pk_add_f32 v[110:111], v[112:113], v[90:91]
	s_andn2_b64 vcc, exec, s[6:7]
	v_pk_add_f32 v[108:109], v[110:111], v[96:97]
	s_mov_b64 s[6:7], -1
	v_pk_add_f32 v[106:107], v[108:109], v[100:101]
	s_nop 0
	v_pk_add_f32 v[104:105], v[106:107], v[102:103]
	ds_write_b64 v58, v[104:105]
	v_add_u32_e32 v58, 0x20a00, v160
	s_waitcnt lgkmcnt(0)
	s_barrier
	ds_read2st64_b64 v[70:73], v58 offset1:1
	ds_read2st64_b64 v[66:69], v58 offset0:2 offset1:3
	ds_read2st64_b64 v[62:65], v58 offset0:4 offset1:5
	ds_read2st64_b64 v[58:61], v58 offset0:6 offset1:7
	s_add_i32 s8, s2, 1
	s_min_u32 s8, s8, 31
	s_lshl_b32 s8, s8, 6
	s_mov_b32 s9, s37
	s_lshl_b64 s[10:11], s[8:9], 13
	v_lshl_add_u64 v[238:239], v[76:77], 0, s[10:11]
	global_load_dwordx2 v[92:93], v[238:239], off nt
	s_add_u32 s10, s10, 0x2000
	s_addc_u32 s11, s11, 0
	v_lshl_add_u64 v[238:239], v[76:77], 0, s[10:11]
	global_load_dwordx2 v[80:81], v[238:239], off nt
	s_add_u32 s10, s10, 0x2000
	s_addc_u32 s11, s11, 0
	v_lshl_add_u64 v[238:239], v[76:77], 0, s[10:11]
	global_load_dwordx2 v[82:83], v[238:239], off nt
	s_add_u32 s10, s10, 0x2000
	s_addc_u32 s11, s11, 0
	v_lshl_add_u64 v[238:239], v[76:77], 0, s[10:11]
	global_load_dwordx2 v[86:87], v[238:239], off nt
	s_add_u32 s10, s10, 0x2000
	s_addc_u32 s11, s11, 0
	v_lshl_add_u64 v[238:239], v[76:77], 0, s[10:11]
	global_load_dwordx2 v[90:91], v[238:239], off nt
	s_add_u32 s10, s10, 0x2000
	s_addc_u32 s11, s11, 0
	v_lshl_add_u64 v[238:239], v[76:77], 0, s[10:11]
	global_load_dwordx2 v[96:97], v[238:239], off nt
	s_add_u32 s10, s10, 0x2000
	s_addc_u32 s11, s11, 0
	v_lshl_add_u64 v[238:239], v[76:77], 0, s[10:11]
	global_load_dwordx2 v[100:101], v[238:239], off nt
	s_add_u32 s10, s10, 0x2000
	s_addc_u32 s11, s11, 0
	v_lshl_add_u64 v[238:239], v[76:77], 0, s[10:11]
	global_load_dwordx2 v[102:103], v[238:239], off nt
	v_add_u32_e32 v242, s19, v74
	s_waitcnt vmcnt(12)
	ds_write_b16 v242, v22
	ds_write_b16_d16_hi v242, v22 offset:144
	ds_write_b16 v242, v23 offset:288
	ds_write_b16_d16_hi v242, v23 offset:432
	ds_write_b16 v242, v24 offset:576
	ds_write_b16_d16_hi v242, v24 offset:720
	ds_write_b16 v242, v25 offset:864
	ds_write_b16_d16_hi v242, v25 offset:1008
	ds_write_b16 v242, v26 offset:1152
	ds_write_b16_d16_hi v242, v26 offset:1296
	ds_write_b16 v242, v27 offset:1440
	ds_write_b16_d16_hi v242, v27 offset:1584
	ds_write_b16 v242, v28 offset:1728
	ds_write_b16_d16_hi v242, v28 offset:1872
	ds_write_b16 v242, v29 offset:2016
	ds_write_b16_d16_hi v242, v29 offset:2160
	s_mul_i32 s10, s8, 0x6000
	s_mov_b32 s11, 0
	v_lshl_add_u64 v[240:241], v[84:85], 0, s[10:11]
	global_load_dwordx4 v[22:25], v[240:241], off
	global_load_dwordx4 v[26:29], v[240:241], off offset:16
	s_waitcnt lgkmcnt(3)
	v_pk_add_f32 v[122:123], v[70:71], 0 op_sel_hi:[1,0]
	s_nop 0
	v_pk_add_f32 v[70:71], v[122:123], v[72:73]
	s_waitcnt lgkmcnt(2)
	v_pk_add_f32 v[70:71], v[70:71], v[66:67]
	s_nop 0
	v_pk_add_f32 v[70:71], v[70:71], v[68:69]
	s_waitcnt lgkmcnt(1)
	v_pk_add_f32 v[120:121], v[70:71], v[62:63]
	s_nop 0
	v_pk_add_f32 v[120:121], v[120:121], v[64:65]
	s_waitcnt lgkmcnt(0)
	v_pk_add_f32 v[120:121], v[120:121], v[58:59]
	s_nop 0
	v_pk_add_f32 v[120:121], v[120:121], v[60:61]
	s_cbranch_vccnz .LBB0_1171
	s_mov_b64 s[6:7], 0

.LBB0_1173:
	v_readlane_b32 s6, v254, 18
	v_readlane_b32 s7, v254, 19
	s_mul_i32 s3, s20, 0x880
	s_nop 0
	v_cndmask_b32_e64 v123, v123, 0, s[6:7]
	v_cndmask_b32_e64 v122, v122, 0, s[6:7]
	v_readlane_b32 s6, v254, 26
	v_pk_add_f32 v[72:73], v[72:73], v[122:123]
	v_readlane_b32 s7, v254, 27
	s_nop 1
	v_cndmask_b32_e64 v73, v123, v73, s[6:7]
	v_cndmask_b32_e64 v72, v122, v72, s[6:7]
	v_readlane_b32 s6, v254, 28
	v_pk_add_f32 v[66:67], v[66:67], v[72:73]
	v_readlane_b32 s7, v254, 29
	s_nop 1
	v_cndmask_b32_e64 v67, v73, v67, s[6:7]
	v_cndmask_b32_e64 v66, v72, v66, s[6:7]
	v_readlane_b32 s6, v254, 30
	v_pk_add_f32 v[68:69], v[68:69], v[66:67]
	v_readlane_b32 s7, v254, 31
	s_nop 1
	v_cndmask_b32_e64 v67, v67, v69, s[6:7]
	v_cndmask_b32_e64 v66, v66, v68, s[6:7]
	v_readlane_b32 s6, v254, 32
	v_pk_add_f32 v[62:63], v[62:63], v[66:67]
	v_readlane_b32 s7, v254, 33
	v_and_b32_e32 v69, 0xffff0000, v125
	v_lshlrev_b32_e32 v68, 16, v125
	v_cndmask_b32_e64 v63, v67, v63, s[6:7]
	v_cndmask_b32_e64 v62, v66, v62, s[6:7]
	v_readlane_b32 s6, v254, 34
	v_pk_add_f32 v[64:65], v[64:65], v[62:63]
	v_readlane_b32 s7, v254, 35
	v_lshlrev_b32_e32 v66, 16, v75
	v_and_b32_e32 v67, 0xffff0000, v75
	s_mov_b32 s10, s8
	s_mul_i32 s10, s10, 0x6000
	s_mov_b32 s11, 0
	v_lshl_add_u64 v[238:239], v[78:79], 0, s[10:11]
	global_load_dword v75, v[238:239], off nt
	s_add_u32 s10, s10, 0x1000
	v_lshl_add_u64 v[240:241], v[78:79], 0, s[10:11]
	global_load_dword v125, v[240:241], off nt
	v_cndmask_b32_e64 v63, v63, v65, s[6:7]
	v_cndmask_b32_e64 v62, v62, v64, s[6:7]
	v_readlane_b32 s6, v254, 36
	v_pk_add_f32 v[58:59], v[58:59], v[62:63]
	v_readlane_b32 s7, v254, 37
	s_nop 1
	v_cndmask_b32_e64 v59, v63, v59, s[6:7]
	v_cndmask_b32_e64 v58, v62, v58, s[6:7]
	v_readlane_b32 s6, v254, 40
	v_pk_add_f32 v[60:61], v[60:61], v[58:59]
	v_readlane_b32 s7, v254, 41
	s_nop 1
	v_cndmask_b32_e64 v58, v58, v60, s[6:7]
	v_sub_f32_e32 v60, v120, v70
	v_cndmask_b32_e64 v59, v59, v61, s[6:7]
	v_exp_f32_e32 v64, v60
	v_sub_f32_e32 v60, v121, v71
	v_exp_f32_e32 v65, v60
	v_pk_add_f32 v[60:61], v[118:119], v[58:59]
	s_nop 0
	v_pk_add_f32 v[62:63], v[60:61], v[70:71] neg_lo:[0,1] neg_hi:[0,1]
	v_exp_f32_e32 v60, v60
	v_min_f32_e32 v73, 0x42e60000, v63
	v_min_f32_e64 v63, -v63, s14
	v_min_f32_e32 v72, 0x42e60000, v62
	v_min_f32_e64 v62, -v62, s14
	v_exp_f32_e32 v63, v63
	v_exp_f32_e32 v72, v72
	v_exp_f32_e32 v73, v73
	v_exp_f32_e32 v62, v62
	v_exp_f32_e32 v61, v61
	v_mul_f32_e32 v63, v63, v69
	v_add_u32_e32 v69, s3, v0
	v_mul_f32_e32 v60, v60, v66
	v_mul_f32_e32 v72, v72, v66
	v_mul_f32_e32 v73, v73, v67
	v_mul_f32_e32 v62, v62, v68
	v_cvt_pk_bf16_f32 v68, v72, v73
	ds_write_b32 v69, v68
	v_mul_f32_e32 v61, v61, v67
	v_cvt_pk_bf16_f32 v60, v60, v61
	ds_write_b32 v69, v60 offset:17408
	v_cvt_pk_bf16_f32 v60, v62, v63
	ds_write_b32 v69, v60 offset:34816
	v_pk_add_f32 v[60:61], v[116:117], v[58:59]
	v_mul_f32_e32 v66, v64, v62
	v_mul_f32_e32 v67, v63, v65
	v_pk_add_f32 v[62:63], v[60:61], v[70:71] neg_lo:[0,1] neg_hi:[0,1]
	v_exp_f32_e32 v60, v60
	v_min_f32_e32 v117, 0x42e60000, v62
	v_min_f32_e32 v118, 0x42e60000, v63
	v_min_f32_e64 v62, -v62, s14
	v_exp_f32_e32 v117, v117
	v_exp_f32_e32 v118, v118
	v_exp_f32_e32 v62, v62
	v_min_f32_e64 v63, -v63, s14
	v_exp_f32_e32 v61, v61
	v_exp_f32_e32 v63, v63
	v_lshlrev_b32_e32 v68, 16, v126
	v_and_b32_e32 v72, 0xffff0000, v126
	v_lshlrev_b32_e32 v73, 16, v127
	v_mul_f32_e32 v60, v60, v68
	v_and_b32_e32 v116, 0xffff0000, v127
	s_or_b32 s10, s8, 1
	s_mul_i32 s10, s10, 0x6000
	s_mov_b32 s11, 0
	v_lshl_add_u64 v[238:239], v[78:79], 0, s[10:11]
	global_load_dword v126, v[238:239], off nt
	s_add_u32 s10, s10, 0x1000
	v_lshl_add_u64 v[240:241], v[78:79], 0, s[10:11]
	global_load_dword v127, v[240:241], off nt
	v_mul_f32_e32 v117, v117, v68
	v_mul_f32_e32 v118, v118, v72
	v_mul_f32_e32 v62, v62, v73
	v_cvt_pk_bf16_f32 v73, v117, v118
	ds_write_b32 v69, v73 offset:272
	v_mul_f32_e32 v61, v61, v72
	v_cvt_pk_bf16_f32 v60, v60, v61
	v_mul_f32_e32 v63, v63, v116
	ds_write_b32 v69, v60 offset:17680
	v_cvt_pk_bf16_f32 v60, v62, v63
	ds_write_b32 v69, v60 offset:35088
	v_pk_add_f32 v[60:61], v[114:115], v[58:59]
	v_mul_f32_e32 v68, v64, v62
	v_mul_f32_e32 v72, v63, v65
	v_pk_add_f32 v[62:63], v[60:61], v[70:71] neg_lo:[0,1] neg_hi:[0,1]
	v_exp_f32_e32 v60, v60
	v_min_f32_e32 v117, 0x42e60000, v62
	v_min_f32_e32 v118, 0x42e60000, v63
	v_min_f32_e64 v62, -v62, s14
	v_exp_f32_e32 v117, v117
	v_exp_f32_e32 v118, v118
	v_exp_f32_e32 v62, v62
	v_min_f32_e64 v63, -v63, s14
	v_exp_f32_e32 v61, v61
	v_exp_f32_e32 v63, v63
	v_lshlrev_b32_e32 v73, 16, v128
	v_and_b32_e32 v114, 0xffff0000, v128
	v_lshlrev_b32_e32 v115, 16, v129
	v_mul_f32_e32 v60, v60, v73
	v_and_b32_e32 v116, 0xffff0000, v129
	s_or_b32 s10, s8, 2
	s_mul_i32 s10, s10, 0x6000
	s_mov_b32 s11, 0
	v_lshl_add_u64 v[238:239], v[78:79], 0, s[10:11]
	global_load_dword v128, v[238:239], off nt
	s_add_u32 s10, s10, 0x1000
	v_lshl_add_u64 v[240:241], v[78:79], 0, s[10:11]
	global_load_dword v129, v[240:241], off nt
	v_mul_f32_e32 v117, v117, v73
	v_mul_f32_e32 v118, v118, v114
	v_mul_f32_e32 v62, v62, v115
	v_cvt_pk_bf16_f32 v115, v117, v118
	ds_write_b32 v69, v115 offset:544
	v_mul_f32_e32 v61, v61, v114
	v_cvt_pk_bf16_f32 v60, v60, v61
	v_mul_f32_e32 v63, v63, v116
	ds_write_b32 v69, v60 offset:17952
	v_cvt_pk_bf16_f32 v60, v62, v63
	ds_write_b32 v69, v60 offset:35360
	v_pk_add_f32 v[60:61], v[112:113], v[58:59]
	v_mul_f32_e32 v73, v64, v62
	v_mul_f32_e32 v114, v63, v65
	v_pk_add_f32 v[62:63], v[60:61], v[70:71] neg_lo:[0,1] neg_hi:[0,1]
	v_exp_f32_e32 v60, v60
	v_min_f32_e32 v117, 0x42e60000, v62
	v_min_f32_e32 v118, 0x42e60000, v63
	v_min_f32_e64 v62, -v62, s14
	v_exp_f32_e32 v117, v117
	v_exp_f32_e32 v118, v118
	v_exp_f32_e32 v62, v62
	v_min_f32_e64 v63, -v63, s14
	v_exp_f32_e32 v61, v61
	v_exp_f32_e32 v63, v63
	v_lshlrev_b32_e32 v112, 16, v130
	v_and_b32_e32 v113, 0xffff0000, v130
	v_lshlrev_b32_e32 v115, 16, v131
	v_mul_f32_e32 v60, v60, v112
	v_and_b32_e32 v116, 0xffff0000, v131
	s_or_b32 s10, s8, 3
	s_mul_i32 s10, s10, 0x6000
	s_mov_b32 s11, 0
	v_lshl_add_u64 v[238:239], v[78:79], 0, s[10:11]
	global_load_dword v130, v[238:239], off nt
	s_add_u32 s10, s10, 0x1000
	v_lshl_add_u64 v[240:241], v[78:79], 0, s[10:11]
	global_load_dword v131, v[240:241], off nt
	v_mul_f32_e32 v117, v117, v112
	v_mul_f32_e32 v118, v118, v113
	v_mul_f32_e32 v62, v62, v115
	v_cvt_pk_bf16_f32 v115, v117, v118
	ds_write_b32 v69, v115 offset:816
	v_mul_f32_e32 v61, v61, v113
	v_cvt_pk_bf16_f32 v60, v60, v61
	v_mul_f32_e32 v63, v63, v116
	ds_write_b32 v69, v60 offset:18224
	v_cvt_pk_bf16_f32 v60, v62, v63
	ds_write_b32 v69, v60 offset:35632
	v_pk_add_f32 v[60:61], v[110:111], v[58:59]
	v_mul_f32_e32 v112, v64, v62
	v_mul_f32_e32 v113, v63, v65
	v_pk_add_f32 v[62:63], v[60:61], v[70:71] neg_lo:[0,1] neg_hi:[0,1]
	v_exp_f32_e32 v60, v60
	v_min_f32_e32 v117, 0x42e60000, v62
	v_min_f32_e32 v118, 0x42e60000, v63
	v_min_f32_e64 v62, -v62, s14
	v_exp_f32_e32 v117, v117
	v_exp_f32_e32 v118, v118
	v_exp_f32_e32 v62, v62
	v_min_f32_e64 v63, -v63, s14
	v_exp_f32_e32 v61, v61
	v_exp_f32_e32 v63, v63
	v_lshlrev_b32_e32 v110, 16, v140
	v_and_b32_e32 v111, 0xffff0000, v140
	v_lshlrev_b32_e32 v115, 16, v142
	v_mul_f32_e32 v60, v60, v110
	v_and_b32_e32 v116, 0xffff0000, v142
	s_or_b32 s10, s8, 4
	s_mul_i32 s10, s10, 0x6000
	s_mov_b32 s11, 0
	v_lshl_add_u64 v[238:239], v[78:79], 0, s[10:11]
	global_load_dword v140, v[238:239], off nt
	s_add_u32 s10, s10, 0x1000
	v_lshl_add_u64 v[240:241], v[78:79], 0, s[10:11]
	global_load_dword v142, v[240:241], off nt
	v_mul_f32_e32 v117, v117, v110
	v_mul_f32_e32 v118, v118, v111
	v_mul_f32_e32 v62, v62, v115
	v_cvt_pk_bf16_f32 v115, v117, v118
	ds_write_b32 v69, v115 offset:1088
	v_mul_f32_e32 v61, v61, v111
	v_cvt_pk_bf16_f32 v60, v60, v61
	v_mul_f32_e32 v63, v63, v116
	ds_write_b32 v69, v60 offset:18496
	v_cvt_pk_bf16_f32 v60, v62, v63
	ds_write_b32 v69, v60 offset:35904
	v_pk_add_f32 v[60:61], v[108:109], v[58:59]
	v_mul_f32_e32 v110, v64, v62
	v_mul_f32_e32 v111, v63, v65
	v_pk_add_f32 v[62:63], v[60:61], v[70:71] neg_lo:[0,1] neg_hi:[0,1]
	v_exp_f32_e32 v60, v60
	v_min_f32_e32 v117, 0x42e60000, v62
	v_min_f32_e32 v118, 0x42e60000, v63
	v_min_f32_e64 v62, -v62, s14
	v_exp_f32_e32 v117, v117
	v_exp_f32_e32 v118, v118
	v_exp_f32_e32 v62, v62
	v_min_f32_e64 v63, -v63, s14
	v_exp_f32_e32 v61, v61
	v_exp_f32_e32 v63, v63
	v_lshlrev_b32_e32 v108, 16, v144
	v_and_b32_e32 v109, 0xffff0000, v144
	v_lshlrev_b32_e32 v115, 16, v149
	v_mul_f32_e32 v60, v60, v108
	v_and_b32_e32 v116, 0xffff0000, v149
	s_or_b32 s10, s8, 5
	s_mul_i32 s10, s10, 0x6000
	s_mov_b32 s11, 0
	v_lshl_add_u64 v[238:239], v[78:79], 0, s[10:11]
	global_load_dword v144, v[238:239], off nt
	s_add_u32 s10, s10, 0x1000
	v_lshl_add_u64 v[240:241], v[78:79], 0, s[10:11]
	global_load_dword v149, v[240:241], off nt
	v_mul_f32_e32 v117, v117, v108
	v_mul_f32_e32 v118, v118, v109
	v_mul_f32_e32 v62, v62, v115
	v_cvt_pk_bf16_f32 v115, v117, v118
	ds_write_b32 v69, v115 offset:1360
	v_mul_f32_e32 v61, v61, v109
	v_cvt_pk_bf16_f32 v60, v60, v61
	v_mul_f32_e32 v63, v63, v116
	ds_write_b32 v69, v60 offset:18768
	v_cvt_pk_bf16_f32 v60, v62, v63
	ds_write_b32 v69, v60 offset:36176
	v_pk_add_f32 v[60:61], v[106:107], v[58:59]
	v_mul_f32_e32 v108, v64, v62
	v_mul_f32_e32 v109, v63, v65
	v_pk_add_f32 v[62:63], v[60:61], v[70:71] neg_lo:[0,1] neg_hi:[0,1]
	v_exp_f32_e32 v60, v60
	v_min_f32_e32 v117, 0x42e60000, v62
	v_min_f32_e32 v118, 0x42e60000, v63
	v_min_f32_e64 v62, -v62, s14
	v_exp_f32_e32 v117, v117
	v_exp_f32_e32 v118, v118
	v_exp_f32_e32 v62, v62
	v_min_f32_e64 v63, -v63, s14
	v_exp_f32_e32 v61, v61
	v_exp_f32_e32 v63, v63
	v_lshlrev_b32_e32 v106, 16, v156
	v_and_b32_e32 v107, 0xffff0000, v156
	v_lshlrev_b32_e32 v115, 16, v157
	v_mul_f32_e32 v60, v60, v106
	v_and_b32_e32 v116, 0xffff0000, v157
	s_or_b32 s10, s8, 6
	s_mul_i32 s10, s10, 0x6000
	s_mov_b32 s11, 0
	v_lshl_add_u64 v[238:239], v[78:79], 0, s[10:11]
	global_load_dword v156, v[238:239], off nt
	s_add_u32 s10, s10, 0x1000
	v_lshl_add_u64 v[240:241], v[78:79], 0, s[10:11]
	global_load_dword v157, v[240:241], off nt
	v_mul_f32_e32 v117, v117, v106
	v_mul_f32_e32 v118, v118, v107
	v_mul_f32_e32 v62, v62, v115
	v_cvt_pk_bf16_f32 v115, v117, v118
	ds_write_b32 v69, v115 offset:1632
	v_mul_f32_e32 v61, v61, v107
	v_cvt_pk_bf16_f32 v60, v60, v61
	v_mul_f32_e32 v63, v63, v116
	ds_write_b32 v69, v60 offset:19040
	v_cvt_pk_bf16_f32 v60, v62, v63
	v_pk_add_f32 v[58:59], v[104:105], v[58:59]
	ds_write_b32 v69, v60 offset:36448
	v_pk_add_f32 v[60:61], v[58:59], v[70:71] neg_lo:[0,1] neg_hi:[0,1]
	v_exp_f32_e32 v58, v58
	v_min_f32_e32 v106, 0x42e60000, v60
	v_min_f32_e32 v107, 0x42e60000, v61
	v_min_f32_e64 v60, -v60, s14
	v_exp_f32_e32 v106, v106
	v_exp_f32_e32 v107, v107
	v_exp_f32_e32 v60, v60
	v_min_f32_e64 v61, -v61, s14
	v_exp_f32_e32 v59, v59
	v_exp_f32_e32 v61, v61
	v_lshlrev_b32_e32 v70, 16, v158
	v_and_b32_e32 v71, 0xffff0000, v158
	v_lshlrev_b32_e32 v104, 16, v159
	v_mul_f32_e32 v58, v58, v70
	v_and_b32_e32 v105, 0xffff0000, v159
	s_or_b32 s10, s8, 7
	s_mul_i32 s10, s10, 0x6000
	s_mov_b32 s11, 0
	v_lshl_add_u64 v[238:239], v[78:79], 0, s[10:11]
	global_load_dword v158, v[238:239], off nt
	s_add_u32 s10, s10, 0x1000
	v_lshl_add_u64 v[240:241], v[78:79], 0, s[10:11]
	global_load_dword v159, v[240:241], off nt
	v_mul_f32_e32 v106, v106, v70
	v_mul_f32_e32 v107, v107, v71
	v_mul_f32_e32 v60, v60, v104
	v_cvt_pk_bf16_f32 v104, v106, v107
	ds_write_b32 v69, v104 offset:1904
	v_mul_f32_e32 v59, v59, v71
	v_cvt_pk_bf16_f32 v58, v58, v59
	v_mul_f32_e32 v61, v61, v105
	ds_write_b32 v69, v58 offset:19312
	v_cvt_pk_bf16_f32 v58, v60, v61
	ds_write_b32 v69, v58 offset:36720
	v_cvt_pk_bf16_f32 v58, v66, v68
	v_mul_f32_e32 v62, v64, v62
	v_mul_f32_e32 v63, v63, v65
	v_mul_f32_e32 v64, v64, v60
	v_mul_f32_e32 v65, v61, v65
	v_cvt_pk_bf16_f32 v59, v73, v112
	v_cvt_pk_bf16_f32 v60, v110, v108
	v_cvt_pk_bf16_f32 v61, v62, v64
	ds_write_b128 v143, v[58:61] offset:52224
	v_cvt_pk_bf16_f32 v58, v67, v72
	s_add_i32 s3, s2, 1
	v_cvt_pk_bf16_f32 v59, v114, v113
	v_cvt_pk_bf16_f32 v60, v111, v109
	v_cvt_pk_bf16_f32 v61, v63, v65
	ds_write_b128 v143, v[58:61] offset:52368
.LBB0_1175:
	v_readlane_b32 s6, v254, 22
	v_readlane_b32 s7, v254, 23
	s_andn2_b64 vcc, exec, s[6:7]
	v_mov_b32_e32 v58, v141
	v_mov_b32_e32 v59, v139
	s_mov_b32 s6, s20
	s_waitcnt lgkmcnt(0)
	s_barrier
	s_cbranch_vccnz .LBB0_1177
